# scan compute role rewritten by hand: 32-step chunk unrolled, 22 VALU per step, transposed y reduction
# speedup vs baseline: 1.0052x; 1.0052x over previous
.LBB0_652:
	s_andn2_saveexec_b64 s[4:5], s[84:85]
	s_cbranch_execz .LBB0_496
	v_mbcnt_lo_u32_b32 v1, -1, 0
	v_mbcnt_hi_u32_b32 v1, -1, v1
	v_mov_b32_e32 v36, 0
	v_mov_b32_e32 v37, 0
	v_mov_b32_e32 v38, 0
	v_mov_b32_e32 v39, 0
	v_lshlrev_b32_e32 v1, 4, v1
	v_add_u32_e32 v1, 0x22000, v1
	s_waitcnt vmcnt(0)
	ds_write_b128 v1, v[36:39]
	s_mov_b32 s6, 0xaaaaaaaa
	s_mov_b32 s7, 0xaaaaaaaa
	s_mov_b32 s10, 0xcccccccc
	s_mov_b32 s11, 0xcccccccc
	v_cmp_eq_u32_e64 s[18:19], 0, v196
	v_mov_b32_e32 v34, 0x17080
	v_add_u32_e32 v35, 0xc200, v207
	v_mov_b64_e32 v[2:3], 0
	v_mov_b64_e32 v[4:5], 0
	v_mov_b64_e32 v[6:7], 0
	v_mov_b64_e32 v[8:9], 0
	v_mov_b32_e32 v14, 0
	s_mov_b32 s0, 0
	s_waitcnt lgkmcnt(0)
	s_barrier
.Lscan_chunk:
	s_and_b32 s1, s0, 1
	s_lshl_b32 s8, s1, 12
	s_mul_i32 s1, s1, 0xb100
	v_add_u32_e32 v30, s1, v197
	v_lshl_add_u32 v31, v195, 2, s1
	v_mov_b32_e32 v1, s1
	v_cndmask_b32_e64 v32, v34, v1, s[18:19]
	v_add_u32_e32 v1, s8, v207
	s_nop 0
	v_cndmask_b32_e64 v33, v35, v1, s[22:23]
	ds_read_b128 v[36:39], v30 offset:24576
	ds_read_b128 v[40:43], v30 offset:24592
	ds_read_b128 v[44:47], v30 offset:16384
	ds_read_b128 v[48:51], v30 offset:16400
	ds_read_b128 v[52:55], v30 offset:32768
	ds_read_b128 v[56:59], v30 offset:32784
	ds_read_b128 v[60:63], v30 offset:0
	ds_read_b128 v[64:67], v30 offset:16
	ds_read_b32 v15, v31 offset:40960
	ds_read_b64 v[18:19], v32 offset:45056
	ds_read_b128 v[68:71], v30 offset:24832
	ds_read_b128 v[72:75], v30 offset:24848
	ds_read_b128 v[76:79], v30 offset:16640
	ds_read_b128 v[80:83], v30 offset:16656
	ds_read_b128 v[84:87], v30 offset:33024
	ds_read_b128 v[88:91], v30 offset:33040
	ds_read_b128 v[134:137], v30 offset:256
	ds_read_b128 v[138:141], v30 offset:272
	ds_read_b32 v17, v31 offset:41088
	ds_read_b64 v[20:21], v32 offset:45064
	s_waitcnt lgkmcnt(10)
	v_pk_mul_f32 v[10:11], v[2:3], v[36:37]
	v_pk_fma_f32 v[10:11], v[4:5], v[38:39], v[10:11]
	v_pk_fma_f32 v[2:3], v[44:45], v[14:15], v[2:3] op_sel:[0,1,0]
	v_pk_fma_f32 v[10:11], v[6:7], v[40:41], v[10:11]
	v_pk_fma_f32 v[4:5], v[46:47], v[14:15], v[4:5] op_sel:[0,1,0]
	v_pk_fma_f32 v[10:11], v[8:9], v[42:43], v[10:11]
	v_pk_fma_f32 v[6:7], v[48:49], v[14:15], v[6:7] op_sel:[0,1,0]
	v_pk_fma_f32 v[10:11], v[14:15], v[18:19], v[10:11]
	v_pk_fma_f32 v[8:9], v[50:51], v[14:15], v[8:9] op_sel:[0,1,0]
	v_add_f32_e32 v10, v10, v11
	v_pk_fma_f32 v[2:3], v[52:53], v[14:15], v[2:3] op_sel_hi:[1,0,1]
	v_pk_fma_f32 v[4:5], v[54:55], v[14:15], v[4:5] op_sel_hi:[1,0,1]
	v_add_f32_dpp v10, v10, v10 quad_perm:[1,0,3,2] row_mask:0xf bank_mask:0xf
	v_pk_fma_f32 v[6:7], v[56:57], v[14:15], v[6:7] op_sel_hi:[1,0,1]
	v_pk_fma_f32 v[8:9], v[58:59], v[14:15], v[8:9] op_sel_hi:[1,0,1]
	v_add_f32_dpp v10, v10, v10 quad_perm:[2,3,0,1] row_mask:0xf bank_mask:0xf
	v_pk_mul_f32 v[12:13], v[2:3], v[60:61]
	v_pk_fma_f32 v[12:13], v[4:5], v[62:63], v[12:13]
	v_add_f32_dpp v16, v10, v10 row_half_mirror row_mask:0xf bank_mask:0xf
	v_pk_fma_f32 v[12:13], v[6:7], v[64:65], v[12:13]
	v_pk_fma_f32 v[12:13], v[8:9], v[66:67], v[12:13]
	v_add_f32_e32 v22, v12, v13
	ds_read_b128 v[36:39], v30 offset:25088
	ds_read_b128 v[40:43], v30 offset:25104
	ds_read_b128 v[44:47], v30 offset:16896
	ds_read_b128 v[48:51], v30 offset:16912
	ds_read_b128 v[52:55], v30 offset:33280
	ds_read_b128 v[56:59], v30 offset:33296
	ds_read_b128 v[60:63], v30 offset:512
	ds_read_b128 v[64:67], v30 offset:528
	ds_read_b32 v15, v31 offset:41216
	ds_read_b64 v[18:19], v32 offset:45072
	s_waitcnt lgkmcnt(10)
	v_pk_mul_f32 v[10:11], v[2:3], v[68:69]
	v_pk_fma_f32 v[10:11], v[4:5], v[70:71], v[10:11]
	v_pk_fma_f32 v[2:3], v[76:77], v[16:17], v[2:3] op_sel:[0,1,0]
	v_pk_fma_f32 v[10:11], v[6:7], v[72:73], v[10:11]
	v_pk_fma_f32 v[4:5], v[78:79], v[16:17], v[4:5] op_sel:[0,1,0]
	v_pk_fma_f32 v[10:11], v[8:9], v[74:75], v[10:11]
	v_pk_fma_f32 v[6:7], v[80:81], v[16:17], v[6:7] op_sel:[0,1,0]
	v_pk_fma_f32 v[10:11], v[16:17], v[20:21], v[10:11]
	v_pk_fma_f32 v[8:9], v[82:83], v[16:17], v[8:9] op_sel:[0,1,0]
	v_add_f32_e32 v10, v10, v11
	v_pk_fma_f32 v[2:3], v[84:85], v[16:17], v[2:3] op_sel_hi:[1,0,1]
	v_pk_fma_f32 v[4:5], v[86:87], v[16:17], v[4:5] op_sel_hi:[1,0,1]
	v_add_f32_dpp v10, v10, v10 quad_perm:[1,0,3,2] row_mask:0xf bank_mask:0xf
	v_pk_fma_f32 v[6:7], v[88:89], v[16:17], v[6:7] op_sel_hi:[1,0,1]
	v_pk_fma_f32 v[8:9], v[90:91], v[16:17], v[8:9] op_sel_hi:[1,0,1]
	v_add_f32_dpp v10, v10, v10 quad_perm:[2,3,0,1] row_mask:0xf bank_mask:0xf
	v_pk_mul_f32 v[12:13], v[2:3], v[134:135]
	v_pk_fma_f32 v[12:13], v[4:5], v[136:137], v[12:13]
	v_add_f32_dpp v14, v10, v10 row_half_mirror row_mask:0xf bank_mask:0xf
	v_pk_fma_f32 v[12:13], v[6:7], v[138:139], v[12:13]
	v_pk_fma_f32 v[12:13], v[8:9], v[140:141], v[12:13]
	v_add_f32_e32 v23, v12, v13
	ds_read_b128 v[68:71], v30 offset:25344
	ds_read_b128 v[72:75], v30 offset:25360
	ds_read_b128 v[76:79], v30 offset:17152
	ds_read_b128 v[80:83], v30 offset:17168
	ds_read_b128 v[84:87], v30 offset:33536
	ds_read_b128 v[88:91], v30 offset:33552
	ds_read_b128 v[134:137], v30 offset:768
	ds_read_b128 v[138:141], v30 offset:784
	ds_read_b32 v17, v31 offset:41344
	ds_read_b64 v[20:21], v32 offset:45080
	s_waitcnt lgkmcnt(10)
	v_pk_mul_f32 v[10:11], v[2:3], v[36:37]
	v_pk_fma_f32 v[10:11], v[4:5], v[38:39], v[10:11]
	v_pk_fma_f32 v[2:3], v[44:45], v[14:15], v[2:3] op_sel:[0,1,0]
	v_pk_fma_f32 v[10:11], v[6:7], v[40:41], v[10:11]
	v_pk_fma_f32 v[4:5], v[46:47], v[14:15], v[4:5] op_sel:[0,1,0]
	v_pk_fma_f32 v[10:11], v[8:9], v[42:43], v[10:11]
	v_pk_fma_f32 v[6:7], v[48:49], v[14:15], v[6:7] op_sel:[0,1,0]
	v_pk_fma_f32 v[10:11], v[14:15], v[18:19], v[10:11]
	v_pk_fma_f32 v[8:9], v[50:51], v[14:15], v[8:9] op_sel:[0,1,0]
	v_add_f32_e32 v10, v10, v11
	v_pk_fma_f32 v[2:3], v[52:53], v[14:15], v[2:3] op_sel_hi:[1,0,1]
	v_pk_fma_f32 v[4:5], v[54:55], v[14:15], v[4:5] op_sel_hi:[1,0,1]
	v_add_f32_dpp v10, v10, v10 quad_perm:[1,0,3,2] row_mask:0xf bank_mask:0xf
	v_pk_fma_f32 v[6:7], v[56:57], v[14:15], v[6:7] op_sel_hi:[1,0,1]
	v_pk_fma_f32 v[8:9], v[58:59], v[14:15], v[8:9] op_sel_hi:[1,0,1]
	v_add_f32_dpp v10, v10, v10 quad_perm:[2,3,0,1] row_mask:0xf bank_mask:0xf
	v_pk_mul_f32 v[12:13], v[2:3], v[60:61]
	v_pk_fma_f32 v[12:13], v[4:5], v[62:63], v[12:13]
	v_add_f32_dpp v16, v10, v10 row_half_mirror row_mask:0xf bank_mask:0xf
	v_pk_fma_f32 v[12:13], v[6:7], v[64:65], v[12:13]
	v_pk_fma_f32 v[12:13], v[8:9], v[66:67], v[12:13]
	v_add_f32_e32 v24, v12, v13
	ds_read_b128 v[36:39], v30 offset:25600
	ds_read_b128 v[40:43], v30 offset:25616
	ds_read_b128 v[44:47], v30 offset:17408
	ds_read_b128 v[48:51], v30 offset:17424
	ds_read_b128 v[52:55], v30 offset:33792
	ds_read_b128 v[56:59], v30 offset:33808
	ds_read_b128 v[60:63], v30 offset:1024
	ds_read_b128 v[64:67], v30 offset:1040
	ds_read_b32 v15, v31 offset:41472
	ds_read_b64 v[18:19], v32 offset:45088
	s_waitcnt lgkmcnt(10)
	v_pk_mul_f32 v[10:11], v[2:3], v[68:69]
	v_pk_fma_f32 v[10:11], v[4:5], v[70:71], v[10:11]
	v_pk_fma_f32 v[2:3], v[76:77], v[16:17], v[2:3] op_sel:[0,1,0]
	v_pk_fma_f32 v[10:11], v[6:7], v[72:73], v[10:11]
	v_pk_fma_f32 v[4:5], v[78:79], v[16:17], v[4:5] op_sel:[0,1,0]
	v_pk_fma_f32 v[10:11], v[8:9], v[74:75], v[10:11]
	v_pk_fma_f32 v[6:7], v[80:81], v[16:17], v[6:7] op_sel:[0,1,0]
	v_pk_fma_f32 v[10:11], v[16:17], v[20:21], v[10:11]
	v_pk_fma_f32 v[8:9], v[82:83], v[16:17], v[8:9] op_sel:[0,1,0]
	v_add_f32_e32 v10, v10, v11
	v_pk_fma_f32 v[2:3], v[84:85], v[16:17], v[2:3] op_sel_hi:[1,0,1]
	v_pk_fma_f32 v[4:5], v[86:87], v[16:17], v[4:5] op_sel_hi:[1,0,1]
	v_add_f32_dpp v10, v10, v10 quad_perm:[1,0,3,2] row_mask:0xf bank_mask:0xf
	v_pk_fma_f32 v[6:7], v[88:89], v[16:17], v[6:7] op_sel_hi:[1,0,1]
	v_pk_fma_f32 v[8:9], v[90:91], v[16:17], v[8:9] op_sel_hi:[1,0,1]
	v_add_f32_dpp v10, v10, v10 quad_perm:[2,3,0,1] row_mask:0xf bank_mask:0xf
	v_pk_mul_f32 v[12:13], v[2:3], v[134:135]
	v_pk_fma_f32 v[12:13], v[4:5], v[136:137], v[12:13]
	v_add_f32_dpp v14, v10, v10 row_half_mirror row_mask:0xf bank_mask:0xf
	v_pk_fma_f32 v[12:13], v[6:7], v[138:139], v[12:13]
	v_pk_fma_f32 v[12:13], v[8:9], v[140:141], v[12:13]
	v_add_f32_e32 v25, v12, v13
	ds_read_b128 v[68:71], v30 offset:25856
	ds_read_b128 v[72:75], v30 offset:25872
	ds_read_b128 v[76:79], v30 offset:17664
	ds_read_b128 v[80:83], v30 offset:17680
	ds_read_b128 v[84:87], v30 offset:34048
	ds_read_b128 v[88:91], v30 offset:34064
	ds_read_b128 v[134:137], v30 offset:1280
	ds_read_b128 v[138:141], v30 offset:1296
	ds_read_b32 v17, v31 offset:41600
	ds_read_b64 v[20:21], v32 offset:45096
	s_waitcnt lgkmcnt(10)
	v_pk_mul_f32 v[10:11], v[2:3], v[36:37]
	v_pk_fma_f32 v[10:11], v[4:5], v[38:39], v[10:11]
	v_cndmask_b32_e64 v26, v22, v23, s[6:7]
	v_cndmask_b32_e64 v27, v23, v22, s[6:7]
	v_pk_fma_f32 v[2:3], v[44:45], v[14:15], v[2:3] op_sel:[0,1,0]
	v_pk_fma_f32 v[10:11], v[6:7], v[40:41], v[10:11]
	v_cndmask_b32_e64 v29, v25, v24, s[6:7]
	v_cndmask_b32_e64 v28, v24, v25, s[6:7]
	v_pk_fma_f32 v[4:5], v[46:47], v[14:15], v[4:5] op_sel:[0,1,0]
	v_pk_fma_f32 v[10:11], v[8:9], v[42:43], v[10:11]
	v_add_f32_dpp v26, v27, v26 quad_perm:[1,0,3,2] row_mask:0xf bank_mask:0xf
	v_pk_fma_f32 v[6:7], v[48:49], v[14:15], v[6:7] op_sel:[0,1,0]
	v_add_f32_dpp v28, v29, v28 quad_perm:[1,0,3,2] row_mask:0xf bank_mask:0xf
	v_pk_fma_f32 v[10:11], v[14:15], v[18:19], v[10:11]
	v_pk_fma_f32 v[8:9], v[50:51], v[14:15], v[8:9] op_sel:[0,1,0]
	v_cndmask_b32_e64 v27, v26, v28, s[10:11]
	v_cndmask_b32_e64 v29, v28, v26, s[10:11]
	v_add_f32_e32 v10, v10, v11
	v_pk_fma_f32 v[2:3], v[52:53], v[14:15], v[2:3] op_sel_hi:[1,0,1]
	v_add_f32_dpp v27, v29, v27 quad_perm:[2,3,0,1] row_mask:0xf bank_mask:0xf
	v_pk_fma_f32 v[4:5], v[54:55], v[14:15], v[4:5] op_sel_hi:[1,0,1]
	v_add_f32_dpp v10, v10, v10 quad_perm:[1,0,3,2] row_mask:0xf bank_mask:0xf
	v_pk_fma_f32 v[6:7], v[56:57], v[14:15], v[6:7] op_sel_hi:[1,0,1]
	v_add_f32_dpp v27, v27, v27 row_shl:4 row_mask:0xf bank_mask:0xf
	v_pk_fma_f32 v[8:9], v[58:59], v[14:15], v[8:9] op_sel_hi:[1,0,1]
	v_add_f32_dpp v10, v10, v10 quad_perm:[2,3,0,1] row_mask:0xf bank_mask:0xf
	v_pk_mul_f32 v[12:13], v[2:3], v[60:61]
	v_pk_fma_f32 v[12:13], v[4:5], v[62:63], v[12:13]
	v_add_f32_dpp v16, v10, v10 row_half_mirror row_mask:0xf bank_mask:0xf
	ds_write_b32 v33, v27 offset:0
	v_pk_fma_f32 v[12:13], v[6:7], v[64:65], v[12:13]
	v_pk_fma_f32 v[12:13], v[8:9], v[66:67], v[12:13]
	v_add_f32_e32 v22, v12, v13
	ds_read_b128 v[36:39], v30 offset:26112
	ds_read_b128 v[40:43], v30 offset:26128
	ds_read_b128 v[44:47], v30 offset:17920
	ds_read_b128 v[48:51], v30 offset:17936
	ds_read_b128 v[52:55], v30 offset:34304
	ds_read_b128 v[56:59], v30 offset:34320
	ds_read_b128 v[60:63], v30 offset:1536
	ds_read_b128 v[64:67], v30 offset:1552
	ds_read_b32 v15, v31 offset:41728
	ds_read_b64 v[18:19], v32 offset:45104
	s_waitcnt lgkmcnt(10)
	v_pk_mul_f32 v[10:11], v[2:3], v[68:69]
	v_pk_fma_f32 v[10:11], v[4:5], v[70:71], v[10:11]
	v_pk_fma_f32 v[2:3], v[76:77], v[16:17], v[2:3] op_sel:[0,1,0]
	v_pk_fma_f32 v[10:11], v[6:7], v[72:73], v[10:11]
	v_pk_fma_f32 v[4:5], v[78:79], v[16:17], v[4:5] op_sel:[0,1,0]
	v_pk_fma_f32 v[10:11], v[8:9], v[74:75], v[10:11]
	v_pk_fma_f32 v[6:7], v[80:81], v[16:17], v[6:7] op_sel:[0,1,0]
	v_pk_fma_f32 v[10:11], v[16:17], v[20:21], v[10:11]
	v_pk_fma_f32 v[8:9], v[82:83], v[16:17], v[8:9] op_sel:[0,1,0]
	v_add_f32_e32 v10, v10, v11
	v_pk_fma_f32 v[2:3], v[84:85], v[16:17], v[2:3] op_sel_hi:[1,0,1]
	v_pk_fma_f32 v[4:5], v[86:87], v[16:17], v[4:5] op_sel_hi:[1,0,1]
	v_add_f32_dpp v10, v10, v10 quad_perm:[1,0,3,2] row_mask:0xf bank_mask:0xf
	v_pk_fma_f32 v[6:7], v[88:89], v[16:17], v[6:7] op_sel_hi:[1,0,1]
	v_pk_fma_f32 v[8:9], v[90:91], v[16:17], v[8:9] op_sel_hi:[1,0,1]
	v_add_f32_dpp v10, v10, v10 quad_perm:[2,3,0,1] row_mask:0xf bank_mask:0xf
	v_pk_mul_f32 v[12:13], v[2:3], v[134:135]
	v_pk_fma_f32 v[12:13], v[4:5], v[136:137], v[12:13]
	v_add_f32_dpp v14, v10, v10 row_half_mirror row_mask:0xf bank_mask:0xf
	v_pk_fma_f32 v[12:13], v[6:7], v[138:139], v[12:13]
	v_pk_fma_f32 v[12:13], v[8:9], v[140:141], v[12:13]
	v_add_f32_e32 v23, v12, v13
	ds_read_b128 v[68:71], v30 offset:26368
	ds_read_b128 v[72:75], v30 offset:26384
	ds_read_b128 v[76:79], v30 offset:18176
	ds_read_b128 v[80:83], v30 offset:18192
	ds_read_b128 v[84:87], v30 offset:34560
	ds_read_b128 v[88:91], v30 offset:34576
	ds_read_b128 v[134:137], v30 offset:1792
	ds_read_b128 v[138:141], v30 offset:1808
	ds_read_b32 v17, v31 offset:41856
	ds_read_b64 v[20:21], v32 offset:45112
	s_waitcnt lgkmcnt(10)
	v_pk_mul_f32 v[10:11], v[2:3], v[36:37]
	v_pk_fma_f32 v[10:11], v[4:5], v[38:39], v[10:11]
	v_pk_fma_f32 v[2:3], v[44:45], v[14:15], v[2:3] op_sel:[0,1,0]
	v_pk_fma_f32 v[10:11], v[6:7], v[40:41], v[10:11]
	v_pk_fma_f32 v[4:5], v[46:47], v[14:15], v[4:5] op_sel:[0,1,0]
	v_pk_fma_f32 v[10:11], v[8:9], v[42:43], v[10:11]
	v_pk_fma_f32 v[6:7], v[48:49], v[14:15], v[6:7] op_sel:[0,1,0]
	v_pk_fma_f32 v[10:11], v[14:15], v[18:19], v[10:11]
	v_pk_fma_f32 v[8:9], v[50:51], v[14:15], v[8:9] op_sel:[0,1,0]
	v_add_f32_e32 v10, v10, v11
	v_pk_fma_f32 v[2:3], v[52:53], v[14:15], v[2:3] op_sel_hi:[1,0,1]
	v_pk_fma_f32 v[4:5], v[54:55], v[14:15], v[4:5] op_sel_hi:[1,0,1]
	v_add_f32_dpp v10, v10, v10 quad_perm:[1,0,3,2] row_mask:0xf bank_mask:0xf
	v_pk_fma_f32 v[6:7], v[56:57], v[14:15], v[6:7] op_sel_hi:[1,0,1]
	v_pk_fma_f32 v[8:9], v[58:59], v[14:15], v[8:9] op_sel_hi:[1,0,1]
	v_add_f32_dpp v10, v10, v10 quad_perm:[2,3,0,1] row_mask:0xf bank_mask:0xf
	v_pk_mul_f32 v[12:13], v[2:3], v[60:61]
	v_pk_fma_f32 v[12:13], v[4:5], v[62:63], v[12:13]
	v_add_f32_dpp v16, v10, v10 row_half_mirror row_mask:0xf bank_mask:0xf
	v_pk_fma_f32 v[12:13], v[6:7], v[64:65], v[12:13]
	v_pk_fma_f32 v[12:13], v[8:9], v[66:67], v[12:13]
	v_add_f32_e32 v24, v12, v13
	ds_read_b128 v[36:39], v30 offset:26624
	ds_read_b128 v[40:43], v30 offset:26640
	ds_read_b128 v[44:47], v30 offset:18432
	ds_read_b128 v[48:51], v30 offset:18448
	ds_read_b128 v[52:55], v30 offset:34816
	ds_read_b128 v[56:59], v30 offset:34832
	ds_read_b128 v[60:63], v30 offset:2048
	ds_read_b128 v[64:67], v30 offset:2064
	ds_read_b32 v15, v31 offset:41984
	ds_read_b64 v[18:19], v32 offset:45120
	s_waitcnt lgkmcnt(10)
	v_pk_mul_f32 v[10:11], v[2:3], v[68:69]
	v_pk_fma_f32 v[10:11], v[4:5], v[70:71], v[10:11]
	v_pk_fma_f32 v[2:3], v[76:77], v[16:17], v[2:3] op_sel:[0,1,0]
	v_pk_fma_f32 v[10:11], v[6:7], v[72:73], v[10:11]
	v_pk_fma_f32 v[4:5], v[78:79], v[16:17], v[4:5] op_sel:[0,1,0]
	v_pk_fma_f32 v[10:11], v[8:9], v[74:75], v[10:11]
	v_pk_fma_f32 v[6:7], v[80:81], v[16:17], v[6:7] op_sel:[0,1,0]
	v_pk_fma_f32 v[10:11], v[16:17], v[20:21], v[10:11]
	v_pk_fma_f32 v[8:9], v[82:83], v[16:17], v[8:9] op_sel:[0,1,0]
	v_add_f32_e32 v10, v10, v11
	v_pk_fma_f32 v[2:3], v[84:85], v[16:17], v[2:3] op_sel_hi:[1,0,1]
	v_pk_fma_f32 v[4:5], v[86:87], v[16:17], v[4:5] op_sel_hi:[1,0,1]
	v_add_f32_dpp v10, v10, v10 quad_perm:[1,0,3,2] row_mask:0xf bank_mask:0xf
	v_pk_fma_f32 v[6:7], v[88:89], v[16:17], v[6:7] op_sel_hi:[1,0,1]
	v_pk_fma_f32 v[8:9], v[90:91], v[16:17], v[8:9] op_sel_hi:[1,0,1]
	v_add_f32_dpp v10, v10, v10 quad_perm:[2,3,0,1] row_mask:0xf bank_mask:0xf
	v_pk_mul_f32 v[12:13], v[2:3], v[134:135]
	v_pk_fma_f32 v[12:13], v[4:5], v[136:137], v[12:13]
	v_add_f32_dpp v14, v10, v10 row_half_mirror row_mask:0xf bank_mask:0xf
	v_pk_fma_f32 v[12:13], v[6:7], v[138:139], v[12:13]
	v_pk_fma_f32 v[12:13], v[8:9], v[140:141], v[12:13]
	v_add_f32_e32 v25, v12, v13
	ds_read_b128 v[68:71], v30 offset:26880
	ds_read_b128 v[72:75], v30 offset:26896
	ds_read_b128 v[76:79], v30 offset:18688
	ds_read_b128 v[80:83], v30 offset:18704
	ds_read_b128 v[84:87], v30 offset:35072
	ds_read_b128 v[88:91], v30 offset:35088
	ds_read_b128 v[134:137], v30 offset:2304
	ds_read_b128 v[138:141], v30 offset:2320
	ds_read_b32 v17, v31 offset:42112
	ds_read_b64 v[20:21], v32 offset:45128
	s_waitcnt lgkmcnt(10)
	v_pk_mul_f32 v[10:11], v[2:3], v[36:37]
	v_pk_fma_f32 v[10:11], v[4:5], v[38:39], v[10:11]
	v_cndmask_b32_e64 v26, v22, v23, s[6:7]
	v_cndmask_b32_e64 v27, v23, v22, s[6:7]
	v_pk_fma_f32 v[2:3], v[44:45], v[14:15], v[2:3] op_sel:[0,1,0]
	v_pk_fma_f32 v[10:11], v[6:7], v[40:41], v[10:11]
	v_cndmask_b32_e64 v29, v25, v24, s[6:7]
	v_cndmask_b32_e64 v28, v24, v25, s[6:7]
	v_pk_fma_f32 v[4:5], v[46:47], v[14:15], v[4:5] op_sel:[0,1,0]
	v_pk_fma_f32 v[10:11], v[8:9], v[42:43], v[10:11]
	v_add_f32_dpp v26, v27, v26 quad_perm:[1,0,3,2] row_mask:0xf bank_mask:0xf
	v_pk_fma_f32 v[6:7], v[48:49], v[14:15], v[6:7] op_sel:[0,1,0]
	v_add_f32_dpp v28, v29, v28 quad_perm:[1,0,3,2] row_mask:0xf bank_mask:0xf
	v_pk_fma_f32 v[10:11], v[14:15], v[18:19], v[10:11]
	v_pk_fma_f32 v[8:9], v[50:51], v[14:15], v[8:9] op_sel:[0,1,0]
	v_cndmask_b32_e64 v27, v26, v28, s[10:11]
	v_cndmask_b32_e64 v29, v28, v26, s[10:11]
	v_add_f32_e32 v10, v10, v11
	v_pk_fma_f32 v[2:3], v[52:53], v[14:15], v[2:3] op_sel_hi:[1,0,1]
	v_add_f32_dpp v27, v29, v27 quad_perm:[2,3,0,1] row_mask:0xf bank_mask:0xf
	v_pk_fma_f32 v[4:5], v[54:55], v[14:15], v[4:5] op_sel_hi:[1,0,1]
	v_add_f32_dpp v10, v10, v10 quad_perm:[1,0,3,2] row_mask:0xf bank_mask:0xf
	v_pk_fma_f32 v[6:7], v[56:57], v[14:15], v[6:7] op_sel_hi:[1,0,1]
	v_add_f32_dpp v27, v27, v27 row_shl:4 row_mask:0xf bank_mask:0xf
	v_pk_fma_f32 v[8:9], v[58:59], v[14:15], v[8:9] op_sel_hi:[1,0,1]
	v_add_f32_dpp v10, v10, v10 quad_perm:[2,3,0,1] row_mask:0xf bank_mask:0xf
	v_pk_mul_f32 v[12:13], v[2:3], v[60:61]
	v_pk_fma_f32 v[12:13], v[4:5], v[62:63], v[12:13]
	v_add_f32_dpp v16, v10, v10 row_half_mirror row_mask:0xf bank_mask:0xf
	ds_write_b32 v33, v27 offset:512
	v_pk_fma_f32 v[12:13], v[6:7], v[64:65], v[12:13]
	v_pk_fma_f32 v[12:13], v[8:9], v[66:67], v[12:13]
	v_add_f32_e32 v22, v12, v13
	ds_read_b128 v[36:39], v30 offset:27136
	ds_read_b128 v[40:43], v30 offset:27152
	ds_read_b128 v[44:47], v30 offset:18944
	ds_read_b128 v[48:51], v30 offset:18960
	ds_read_b128 v[52:55], v30 offset:35328
	ds_read_b128 v[56:59], v30 offset:35344
	ds_read_b128 v[60:63], v30 offset:2560
	ds_read_b128 v[64:67], v30 offset:2576
	ds_read_b32 v15, v31 offset:42240
	ds_read_b64 v[18:19], v32 offset:45136
	s_waitcnt lgkmcnt(10)
	v_pk_mul_f32 v[10:11], v[2:3], v[68:69]
	v_pk_fma_f32 v[10:11], v[4:5], v[70:71], v[10:11]
	v_pk_fma_f32 v[2:3], v[76:77], v[16:17], v[2:3] op_sel:[0,1,0]
	v_pk_fma_f32 v[10:11], v[6:7], v[72:73], v[10:11]
	v_pk_fma_f32 v[4:5], v[78:79], v[16:17], v[4:5] op_sel:[0,1,0]
	v_pk_fma_f32 v[10:11], v[8:9], v[74:75], v[10:11]
	v_pk_fma_f32 v[6:7], v[80:81], v[16:17], v[6:7] op_sel:[0,1,0]
	v_pk_fma_f32 v[10:11], v[16:17], v[20:21], v[10:11]
	v_pk_fma_f32 v[8:9], v[82:83], v[16:17], v[8:9] op_sel:[0,1,0]
	v_add_f32_e32 v10, v10, v11
	v_pk_fma_f32 v[2:3], v[84:85], v[16:17], v[2:3] op_sel_hi:[1,0,1]
	v_pk_fma_f32 v[4:5], v[86:87], v[16:17], v[4:5] op_sel_hi:[1,0,1]
	v_add_f32_dpp v10, v10, v10 quad_perm:[1,0,3,2] row_mask:0xf bank_mask:0xf
	v_pk_fma_f32 v[6:7], v[88:89], v[16:17], v[6:7] op_sel_hi:[1,0,1]
	v_pk_fma_f32 v[8:9], v[90:91], v[16:17], v[8:9] op_sel_hi:[1,0,1]
	v_add_f32_dpp v10, v10, v10 quad_perm:[2,3,0,1] row_mask:0xf bank_mask:0xf
	v_pk_mul_f32 v[12:13], v[2:3], v[134:135]
	v_pk_fma_f32 v[12:13], v[4:5], v[136:137], v[12:13]
	v_add_f32_dpp v14, v10, v10 row_half_mirror row_mask:0xf bank_mask:0xf
	v_pk_fma_f32 v[12:13], v[6:7], v[138:139], v[12:13]
	v_pk_fma_f32 v[12:13], v[8:9], v[140:141], v[12:13]
	v_add_f32_e32 v23, v12, v13
	ds_read_b128 v[68:71], v30 offset:27392
	ds_read_b128 v[72:75], v30 offset:27408
	ds_read_b128 v[76:79], v30 offset:19200
	ds_read_b128 v[80:83], v30 offset:19216
	ds_read_b128 v[84:87], v30 offset:35584
	ds_read_b128 v[88:91], v30 offset:35600
	ds_read_b128 v[134:137], v30 offset:2816
	ds_read_b128 v[138:141], v30 offset:2832
	ds_read_b32 v17, v31 offset:42368
	ds_read_b64 v[20:21], v32 offset:45144
	s_waitcnt lgkmcnt(10)
	v_pk_mul_f32 v[10:11], v[2:3], v[36:37]
	v_pk_fma_f32 v[10:11], v[4:5], v[38:39], v[10:11]
	v_pk_fma_f32 v[2:3], v[44:45], v[14:15], v[2:3] op_sel:[0,1,0]
	v_pk_fma_f32 v[10:11], v[6:7], v[40:41], v[10:11]
	v_pk_fma_f32 v[4:5], v[46:47], v[14:15], v[4:5] op_sel:[0,1,0]
	v_pk_fma_f32 v[10:11], v[8:9], v[42:43], v[10:11]
	v_pk_fma_f32 v[6:7], v[48:49], v[14:15], v[6:7] op_sel:[0,1,0]
	v_pk_fma_f32 v[10:11], v[14:15], v[18:19], v[10:11]
	v_pk_fma_f32 v[8:9], v[50:51], v[14:15], v[8:9] op_sel:[0,1,0]
	v_add_f32_e32 v10, v10, v11
	v_pk_fma_f32 v[2:3], v[52:53], v[14:15], v[2:3] op_sel_hi:[1,0,1]
	v_pk_fma_f32 v[4:5], v[54:55], v[14:15], v[4:5] op_sel_hi:[1,0,1]
	v_add_f32_dpp v10, v10, v10 quad_perm:[1,0,3,2] row_mask:0xf bank_mask:0xf
	v_pk_fma_f32 v[6:7], v[56:57], v[14:15], v[6:7] op_sel_hi:[1,0,1]
	v_pk_fma_f32 v[8:9], v[58:59], v[14:15], v[8:9] op_sel_hi:[1,0,1]
	v_add_f32_dpp v10, v10, v10 quad_perm:[2,3,0,1] row_mask:0xf bank_mask:0xf
	v_pk_mul_f32 v[12:13], v[2:3], v[60:61]
	v_pk_fma_f32 v[12:13], v[4:5], v[62:63], v[12:13]
	v_add_f32_dpp v16, v10, v10 row_half_mirror row_mask:0xf bank_mask:0xf
	v_pk_fma_f32 v[12:13], v[6:7], v[64:65], v[12:13]
	v_pk_fma_f32 v[12:13], v[8:9], v[66:67], v[12:13]
	v_add_f32_e32 v24, v12, v13
	ds_read_b128 v[36:39], v30 offset:27648
	ds_read_b128 v[40:43], v30 offset:27664
	ds_read_b128 v[44:47], v30 offset:19456
	ds_read_b128 v[48:51], v30 offset:19472
	ds_read_b128 v[52:55], v30 offset:35840
	ds_read_b128 v[56:59], v30 offset:35856
	ds_read_b128 v[60:63], v30 offset:3072
	ds_read_b128 v[64:67], v30 offset:3088
	ds_read_b32 v15, v31 offset:42496
	ds_read_b64 v[18:19], v32 offset:45152
	s_waitcnt lgkmcnt(10)
	v_pk_mul_f32 v[10:11], v[2:3], v[68:69]
	v_pk_fma_f32 v[10:11], v[4:5], v[70:71], v[10:11]
	v_pk_fma_f32 v[2:3], v[76:77], v[16:17], v[2:3] op_sel:[0,1,0]
	v_pk_fma_f32 v[10:11], v[6:7], v[72:73], v[10:11]
	v_pk_fma_f32 v[4:5], v[78:79], v[16:17], v[4:5] op_sel:[0,1,0]
	v_pk_fma_f32 v[10:11], v[8:9], v[74:75], v[10:11]
	v_pk_fma_f32 v[6:7], v[80:81], v[16:17], v[6:7] op_sel:[0,1,0]
	v_pk_fma_f32 v[10:11], v[16:17], v[20:21], v[10:11]
	v_pk_fma_f32 v[8:9], v[82:83], v[16:17], v[8:9] op_sel:[0,1,0]
	v_add_f32_e32 v10, v10, v11
	v_pk_fma_f32 v[2:3], v[84:85], v[16:17], v[2:3] op_sel_hi:[1,0,1]
	v_pk_fma_f32 v[4:5], v[86:87], v[16:17], v[4:5] op_sel_hi:[1,0,1]
	v_add_f32_dpp v10, v10, v10 quad_perm:[1,0,3,2] row_mask:0xf bank_mask:0xf
	v_pk_fma_f32 v[6:7], v[88:89], v[16:17], v[6:7] op_sel_hi:[1,0,1]
	v_pk_fma_f32 v[8:9], v[90:91], v[16:17], v[8:9] op_sel_hi:[1,0,1]
	v_add_f32_dpp v10, v10, v10 quad_perm:[2,3,0,1] row_mask:0xf bank_mask:0xf
	v_pk_mul_f32 v[12:13], v[2:3], v[134:135]
	v_pk_fma_f32 v[12:13], v[4:5], v[136:137], v[12:13]
	v_add_f32_dpp v14, v10, v10 row_half_mirror row_mask:0xf bank_mask:0xf
	v_pk_fma_f32 v[12:13], v[6:7], v[138:139], v[12:13]
	v_pk_fma_f32 v[12:13], v[8:9], v[140:141], v[12:13]
	v_add_f32_e32 v25, v12, v13
	ds_read_b128 v[68:71], v30 offset:27904
	ds_read_b128 v[72:75], v30 offset:27920
	ds_read_b128 v[76:79], v30 offset:19712
	ds_read_b128 v[80:83], v30 offset:19728
	ds_read_b128 v[84:87], v30 offset:36096
	ds_read_b128 v[88:91], v30 offset:36112
	ds_read_b128 v[134:137], v30 offset:3328
	ds_read_b128 v[138:141], v30 offset:3344
	ds_read_b32 v17, v31 offset:42624
	ds_read_b64 v[20:21], v32 offset:45160
	s_waitcnt lgkmcnt(10)
	v_pk_mul_f32 v[10:11], v[2:3], v[36:37]
	v_pk_fma_f32 v[10:11], v[4:5], v[38:39], v[10:11]
	v_cndmask_b32_e64 v26, v22, v23, s[6:7]
	v_cndmask_b32_e64 v27, v23, v22, s[6:7]
	v_pk_fma_f32 v[2:3], v[44:45], v[14:15], v[2:3] op_sel:[0,1,0]
	v_pk_fma_f32 v[10:11], v[6:7], v[40:41], v[10:11]
	v_cndmask_b32_e64 v29, v25, v24, s[6:7]
	v_cndmask_b32_e64 v28, v24, v25, s[6:7]
	v_pk_fma_f32 v[4:5], v[46:47], v[14:15], v[4:5] op_sel:[0,1,0]
	v_pk_fma_f32 v[10:11], v[8:9], v[42:43], v[10:11]
	v_add_f32_dpp v26, v27, v26 quad_perm:[1,0,3,2] row_mask:0xf bank_mask:0xf
	v_pk_fma_f32 v[6:7], v[48:49], v[14:15], v[6:7] op_sel:[0,1,0]
	v_add_f32_dpp v28, v29, v28 quad_perm:[1,0,3,2] row_mask:0xf bank_mask:0xf
	v_pk_fma_f32 v[10:11], v[14:15], v[18:19], v[10:11]
	v_pk_fma_f32 v[8:9], v[50:51], v[14:15], v[8:9] op_sel:[0,1,0]
	v_cndmask_b32_e64 v27, v26, v28, s[10:11]
	v_cndmask_b32_e64 v29, v28, v26, s[10:11]
	v_add_f32_e32 v10, v10, v11
	v_pk_fma_f32 v[2:3], v[52:53], v[14:15], v[2:3] op_sel_hi:[1,0,1]
	v_add_f32_dpp v27, v29, v27 quad_perm:[2,3,0,1] row_mask:0xf bank_mask:0xf
	v_pk_fma_f32 v[4:5], v[54:55], v[14:15], v[4:5] op_sel_hi:[1,0,1]
	v_add_f32_dpp v10, v10, v10 quad_perm:[1,0,3,2] row_mask:0xf bank_mask:0xf
	v_pk_fma_f32 v[6:7], v[56:57], v[14:15], v[6:7] op_sel_hi:[1,0,1]
	v_add_f32_dpp v27, v27, v27 row_shl:4 row_mask:0xf bank_mask:0xf
	v_pk_fma_f32 v[8:9], v[58:59], v[14:15], v[8:9] op_sel_hi:[1,0,1]
	v_add_f32_dpp v10, v10, v10 quad_perm:[2,3,0,1] row_mask:0xf bank_mask:0xf
	v_pk_mul_f32 v[12:13], v[2:3], v[60:61]
	v_pk_fma_f32 v[12:13], v[4:5], v[62:63], v[12:13]
	v_add_f32_dpp v16, v10, v10 row_half_mirror row_mask:0xf bank_mask:0xf
	ds_write_b32 v33, v27 offset:1024
	v_pk_fma_f32 v[12:13], v[6:7], v[64:65], v[12:13]
	v_pk_fma_f32 v[12:13], v[8:9], v[66:67], v[12:13]
	v_add_f32_e32 v22, v12, v13
	ds_read_b128 v[36:39], v30 offset:28160
	ds_read_b128 v[40:43], v30 offset:28176
	ds_read_b128 v[44:47], v30 offset:19968
	ds_read_b128 v[48:51], v30 offset:19984
	ds_read_b128 v[52:55], v30 offset:36352
	ds_read_b128 v[56:59], v30 offset:36368
	ds_read_b128 v[60:63], v30 offset:3584
	ds_read_b128 v[64:67], v30 offset:3600
	ds_read_b32 v15, v31 offset:42752
	ds_read_b64 v[18:19], v32 offset:45168
	s_waitcnt lgkmcnt(10)
	v_pk_mul_f32 v[10:11], v[2:3], v[68:69]
	v_pk_fma_f32 v[10:11], v[4:5], v[70:71], v[10:11]
	v_pk_fma_f32 v[2:3], v[76:77], v[16:17], v[2:3] op_sel:[0,1,0]
	v_pk_fma_f32 v[10:11], v[6:7], v[72:73], v[10:11]
	v_pk_fma_f32 v[4:5], v[78:79], v[16:17], v[4:5] op_sel:[0,1,0]
	v_pk_fma_f32 v[10:11], v[8:9], v[74:75], v[10:11]
	v_pk_fma_f32 v[6:7], v[80:81], v[16:17], v[6:7] op_sel:[0,1,0]
	v_pk_fma_f32 v[10:11], v[16:17], v[20:21], v[10:11]
	v_pk_fma_f32 v[8:9], v[82:83], v[16:17], v[8:9] op_sel:[0,1,0]
	v_add_f32_e32 v10, v10, v11
	v_pk_fma_f32 v[2:3], v[84:85], v[16:17], v[2:3] op_sel_hi:[1,0,1]
	v_pk_fma_f32 v[4:5], v[86:87], v[16:17], v[4:5] op_sel_hi:[1,0,1]
	v_add_f32_dpp v10, v10, v10 quad_perm:[1,0,3,2] row_mask:0xf bank_mask:0xf
	v_pk_fma_f32 v[6:7], v[88:89], v[16:17], v[6:7] op_sel_hi:[1,0,1]
	v_pk_fma_f32 v[8:9], v[90:91], v[16:17], v[8:9] op_sel_hi:[1,0,1]
	v_add_f32_dpp v10, v10, v10 quad_perm:[2,3,0,1] row_mask:0xf bank_mask:0xf
	v_pk_mul_f32 v[12:13], v[2:3], v[134:135]
	v_pk_fma_f32 v[12:13], v[4:5], v[136:137], v[12:13]
	v_add_f32_dpp v14, v10, v10 row_half_mirror row_mask:0xf bank_mask:0xf
	v_pk_fma_f32 v[12:13], v[6:7], v[138:139], v[12:13]
	v_pk_fma_f32 v[12:13], v[8:9], v[140:141], v[12:13]
	v_add_f32_e32 v23, v12, v13
	ds_read_b128 v[68:71], v30 offset:28416
	ds_read_b128 v[72:75], v30 offset:28432
	ds_read_b128 v[76:79], v30 offset:20224
	ds_read_b128 v[80:83], v30 offset:20240
	ds_read_b128 v[84:87], v30 offset:36608
	ds_read_b128 v[88:91], v30 offset:36624
	ds_read_b128 v[134:137], v30 offset:3840
	ds_read_b128 v[138:141], v30 offset:3856
	ds_read_b32 v17, v31 offset:42880
	ds_read_b64 v[20:21], v32 offset:45176
	s_waitcnt lgkmcnt(10)
	v_pk_mul_f32 v[10:11], v[2:3], v[36:37]
	v_pk_fma_f32 v[10:11], v[4:5], v[38:39], v[10:11]
	v_pk_fma_f32 v[2:3], v[44:45], v[14:15], v[2:3] op_sel:[0,1,0]
	v_pk_fma_f32 v[10:11], v[6:7], v[40:41], v[10:11]
	v_pk_fma_f32 v[4:5], v[46:47], v[14:15], v[4:5] op_sel:[0,1,0]
	v_pk_fma_f32 v[10:11], v[8:9], v[42:43], v[10:11]
	v_pk_fma_f32 v[6:7], v[48:49], v[14:15], v[6:7] op_sel:[0,1,0]
	v_pk_fma_f32 v[10:11], v[14:15], v[18:19], v[10:11]
	v_pk_fma_f32 v[8:9], v[50:51], v[14:15], v[8:9] op_sel:[0,1,0]
	v_add_f32_e32 v10, v10, v11
	v_pk_fma_f32 v[2:3], v[52:53], v[14:15], v[2:3] op_sel_hi:[1,0,1]
	v_pk_fma_f32 v[4:5], v[54:55], v[14:15], v[4:5] op_sel_hi:[1,0,1]
	v_add_f32_dpp v10, v10, v10 quad_perm:[1,0,3,2] row_mask:0xf bank_mask:0xf
	v_pk_fma_f32 v[6:7], v[56:57], v[14:15], v[6:7] op_sel_hi:[1,0,1]
	v_pk_fma_f32 v[8:9], v[58:59], v[14:15], v[8:9] op_sel_hi:[1,0,1]
	v_add_f32_dpp v10, v10, v10 quad_perm:[2,3,0,1] row_mask:0xf bank_mask:0xf
	v_pk_mul_f32 v[12:13], v[2:3], v[60:61]
	v_pk_fma_f32 v[12:13], v[4:5], v[62:63], v[12:13]
	v_add_f32_dpp v16, v10, v10 row_half_mirror row_mask:0xf bank_mask:0xf
	v_pk_fma_f32 v[12:13], v[6:7], v[64:65], v[12:13]
	v_pk_fma_f32 v[12:13], v[8:9], v[66:67], v[12:13]
	v_add_f32_e32 v24, v12, v13
	ds_read_b128 v[36:39], v30 offset:28672
	ds_read_b128 v[40:43], v30 offset:28688
	ds_read_b128 v[44:47], v30 offset:20480
	ds_read_b128 v[48:51], v30 offset:20496
	ds_read_b128 v[52:55], v30 offset:36864
	ds_read_b128 v[56:59], v30 offset:36880
	ds_read_b128 v[60:63], v30 offset:4096
	ds_read_b128 v[64:67], v30 offset:4112
	ds_read_b32 v15, v31 offset:43008
	ds_read_b64 v[18:19], v32 offset:45184
	s_waitcnt lgkmcnt(10)
	v_pk_mul_f32 v[10:11], v[2:3], v[68:69]
	v_pk_fma_f32 v[10:11], v[4:5], v[70:71], v[10:11]
	v_pk_fma_f32 v[2:3], v[76:77], v[16:17], v[2:3] op_sel:[0,1,0]
	v_pk_fma_f32 v[10:11], v[6:7], v[72:73], v[10:11]
	v_pk_fma_f32 v[4:5], v[78:79], v[16:17], v[4:5] op_sel:[0,1,0]
	v_pk_fma_f32 v[10:11], v[8:9], v[74:75], v[10:11]
	v_pk_fma_f32 v[6:7], v[80:81], v[16:17], v[6:7] op_sel:[0,1,0]
	v_pk_fma_f32 v[10:11], v[16:17], v[20:21], v[10:11]
	v_pk_fma_f32 v[8:9], v[82:83], v[16:17], v[8:9] op_sel:[0,1,0]
	v_add_f32_e32 v10, v10, v11
	v_pk_fma_f32 v[2:3], v[84:85], v[16:17], v[2:3] op_sel_hi:[1,0,1]
	v_pk_fma_f32 v[4:5], v[86:87], v[16:17], v[4:5] op_sel_hi:[1,0,1]
	v_add_f32_dpp v10, v10, v10 quad_perm:[1,0,3,2] row_mask:0xf bank_mask:0xf
	v_pk_fma_f32 v[6:7], v[88:89], v[16:17], v[6:7] op_sel_hi:[1,0,1]
	v_pk_fma_f32 v[8:9], v[90:91], v[16:17], v[8:9] op_sel_hi:[1,0,1]
	v_add_f32_dpp v10, v10, v10 quad_perm:[2,3,0,1] row_mask:0xf bank_mask:0xf
	v_pk_mul_f32 v[12:13], v[2:3], v[134:135]
	v_pk_fma_f32 v[12:13], v[4:5], v[136:137], v[12:13]
	v_add_f32_dpp v14, v10, v10 row_half_mirror row_mask:0xf bank_mask:0xf
	v_pk_fma_f32 v[12:13], v[6:7], v[138:139], v[12:13]
	v_pk_fma_f32 v[12:13], v[8:9], v[140:141], v[12:13]
	v_add_f32_e32 v25, v12, v13
	ds_read_b128 v[68:71], v30 offset:28928
	ds_read_b128 v[72:75], v30 offset:28944
	ds_read_b128 v[76:79], v30 offset:20736
	ds_read_b128 v[80:83], v30 offset:20752
	ds_read_b128 v[84:87], v30 offset:37120
	ds_read_b128 v[88:91], v30 offset:37136
	ds_read_b128 v[134:137], v30 offset:4352
	ds_read_b128 v[138:141], v30 offset:4368
	ds_read_b32 v17, v31 offset:43136
	ds_read_b64 v[20:21], v32 offset:45192
	s_waitcnt lgkmcnt(10)
	v_pk_mul_f32 v[10:11], v[2:3], v[36:37]
	v_pk_fma_f32 v[10:11], v[4:5], v[38:39], v[10:11]
	v_cndmask_b32_e64 v26, v22, v23, s[6:7]
	v_cndmask_b32_e64 v27, v23, v22, s[6:7]
	v_pk_fma_f32 v[2:3], v[44:45], v[14:15], v[2:3] op_sel:[0,1,0]
	v_pk_fma_f32 v[10:11], v[6:7], v[40:41], v[10:11]
	v_cndmask_b32_e64 v29, v25, v24, s[6:7]
	v_cndmask_b32_e64 v28, v24, v25, s[6:7]
	v_pk_fma_f32 v[4:5], v[46:47], v[14:15], v[4:5] op_sel:[0,1,0]
	v_pk_fma_f32 v[10:11], v[8:9], v[42:43], v[10:11]
	v_add_f32_dpp v26, v27, v26 quad_perm:[1,0,3,2] row_mask:0xf bank_mask:0xf
	v_pk_fma_f32 v[6:7], v[48:49], v[14:15], v[6:7] op_sel:[0,1,0]
	v_add_f32_dpp v28, v29, v28 quad_perm:[1,0,3,2] row_mask:0xf bank_mask:0xf
	v_pk_fma_f32 v[10:11], v[14:15], v[18:19], v[10:11]
	v_pk_fma_f32 v[8:9], v[50:51], v[14:15], v[8:9] op_sel:[0,1,0]
	v_cndmask_b32_e64 v27, v26, v28, s[10:11]
	v_cndmask_b32_e64 v29, v28, v26, s[10:11]
	v_add_f32_e32 v10, v10, v11
	v_pk_fma_f32 v[2:3], v[52:53], v[14:15], v[2:3] op_sel_hi:[1,0,1]
	v_add_f32_dpp v27, v29, v27 quad_perm:[2,3,0,1] row_mask:0xf bank_mask:0xf
	v_pk_fma_f32 v[4:5], v[54:55], v[14:15], v[4:5] op_sel_hi:[1,0,1]
	v_add_f32_dpp v10, v10, v10 quad_perm:[1,0,3,2] row_mask:0xf bank_mask:0xf
	v_pk_fma_f32 v[6:7], v[56:57], v[14:15], v[6:7] op_sel_hi:[1,0,1]
	v_add_f32_dpp v27, v27, v27 row_shl:4 row_mask:0xf bank_mask:0xf
	v_pk_fma_f32 v[8:9], v[58:59], v[14:15], v[8:9] op_sel_hi:[1,0,1]
	v_add_f32_dpp v10, v10, v10 quad_perm:[2,3,0,1] row_mask:0xf bank_mask:0xf
	v_pk_mul_f32 v[12:13], v[2:3], v[60:61]
	v_pk_fma_f32 v[12:13], v[4:5], v[62:63], v[12:13]
	v_add_f32_dpp v16, v10, v10 row_half_mirror row_mask:0xf bank_mask:0xf
	ds_write_b32 v33, v27 offset:1536
	v_pk_fma_f32 v[12:13], v[6:7], v[64:65], v[12:13]
	v_pk_fma_f32 v[12:13], v[8:9], v[66:67], v[12:13]
	v_add_f32_e32 v22, v12, v13
	ds_read_b128 v[36:39], v30 offset:29184
	ds_read_b128 v[40:43], v30 offset:29200
	ds_read_b128 v[44:47], v30 offset:20992
	ds_read_b128 v[48:51], v30 offset:21008
	ds_read_b128 v[52:55], v30 offset:37376
	ds_read_b128 v[56:59], v30 offset:37392
	ds_read_b128 v[60:63], v30 offset:4608
	ds_read_b128 v[64:67], v30 offset:4624
	ds_read_b32 v15, v31 offset:43264
	ds_read_b64 v[18:19], v32 offset:45200
	s_waitcnt lgkmcnt(10)
	v_pk_mul_f32 v[10:11], v[2:3], v[68:69]
	v_pk_fma_f32 v[10:11], v[4:5], v[70:71], v[10:11]
	v_pk_fma_f32 v[2:3], v[76:77], v[16:17], v[2:3] op_sel:[0,1,0]
	v_pk_fma_f32 v[10:11], v[6:7], v[72:73], v[10:11]
	v_pk_fma_f32 v[4:5], v[78:79], v[16:17], v[4:5] op_sel:[0,1,0]
	v_pk_fma_f32 v[10:11], v[8:9], v[74:75], v[10:11]
	v_pk_fma_f32 v[6:7], v[80:81], v[16:17], v[6:7] op_sel:[0,1,0]
	v_pk_fma_f32 v[10:11], v[16:17], v[20:21], v[10:11]
	v_pk_fma_f32 v[8:9], v[82:83], v[16:17], v[8:9] op_sel:[0,1,0]
	v_add_f32_e32 v10, v10, v11
	v_pk_fma_f32 v[2:3], v[84:85], v[16:17], v[2:3] op_sel_hi:[1,0,1]
	v_pk_fma_f32 v[4:5], v[86:87], v[16:17], v[4:5] op_sel_hi:[1,0,1]
	v_add_f32_dpp v10, v10, v10 quad_perm:[1,0,3,2] row_mask:0xf bank_mask:0xf
	v_pk_fma_f32 v[6:7], v[88:89], v[16:17], v[6:7] op_sel_hi:[1,0,1]
	v_pk_fma_f32 v[8:9], v[90:91], v[16:17], v[8:9] op_sel_hi:[1,0,1]
	v_add_f32_dpp v10, v10, v10 quad_perm:[2,3,0,1] row_mask:0xf bank_mask:0xf
	v_pk_mul_f32 v[12:13], v[2:3], v[134:135]
	v_pk_fma_f32 v[12:13], v[4:5], v[136:137], v[12:13]
	v_add_f32_dpp v14, v10, v10 row_half_mirror row_mask:0xf bank_mask:0xf
	v_pk_fma_f32 v[12:13], v[6:7], v[138:139], v[12:13]
	v_pk_fma_f32 v[12:13], v[8:9], v[140:141], v[12:13]
	v_add_f32_e32 v23, v12, v13
	ds_read_b128 v[68:71], v30 offset:29440
	ds_read_b128 v[72:75], v30 offset:29456
	ds_read_b128 v[76:79], v30 offset:21248
	ds_read_b128 v[80:83], v30 offset:21264
	ds_read_b128 v[84:87], v30 offset:37632
	ds_read_b128 v[88:91], v30 offset:37648
	ds_read_b128 v[134:137], v30 offset:4864
	ds_read_b128 v[138:141], v30 offset:4880
	ds_read_b32 v17, v31 offset:43392
	ds_read_b64 v[20:21], v32 offset:45208
	s_waitcnt lgkmcnt(10)
	v_pk_mul_f32 v[10:11], v[2:3], v[36:37]
	v_pk_fma_f32 v[10:11], v[4:5], v[38:39], v[10:11]
	v_pk_fma_f32 v[2:3], v[44:45], v[14:15], v[2:3] op_sel:[0,1,0]
	v_pk_fma_f32 v[10:11], v[6:7], v[40:41], v[10:11]
	v_pk_fma_f32 v[4:5], v[46:47], v[14:15], v[4:5] op_sel:[0,1,0]
	v_pk_fma_f32 v[10:11], v[8:9], v[42:43], v[10:11]
	v_pk_fma_f32 v[6:7], v[48:49], v[14:15], v[6:7] op_sel:[0,1,0]
	v_pk_fma_f32 v[10:11], v[14:15], v[18:19], v[10:11]
	v_pk_fma_f32 v[8:9], v[50:51], v[14:15], v[8:9] op_sel:[0,1,0]
	v_add_f32_e32 v10, v10, v11
	v_pk_fma_f32 v[2:3], v[52:53], v[14:15], v[2:3] op_sel_hi:[1,0,1]
	v_pk_fma_f32 v[4:5], v[54:55], v[14:15], v[4:5] op_sel_hi:[1,0,1]
	v_add_f32_dpp v10, v10, v10 quad_perm:[1,0,3,2] row_mask:0xf bank_mask:0xf
	v_pk_fma_f32 v[6:7], v[56:57], v[14:15], v[6:7] op_sel_hi:[1,0,1]
	v_pk_fma_f32 v[8:9], v[58:59], v[14:15], v[8:9] op_sel_hi:[1,0,1]
	v_add_f32_dpp v10, v10, v10 quad_perm:[2,3,0,1] row_mask:0xf bank_mask:0xf
	v_pk_mul_f32 v[12:13], v[2:3], v[60:61]
	v_pk_fma_f32 v[12:13], v[4:5], v[62:63], v[12:13]
	v_add_f32_dpp v16, v10, v10 row_half_mirror row_mask:0xf bank_mask:0xf
	v_pk_fma_f32 v[12:13], v[6:7], v[64:65], v[12:13]
	v_pk_fma_f32 v[12:13], v[8:9], v[66:67], v[12:13]
	v_add_f32_e32 v24, v12, v13
	ds_read_b128 v[36:39], v30 offset:29696
	ds_read_b128 v[40:43], v30 offset:29712
	ds_read_b128 v[44:47], v30 offset:21504
	ds_read_b128 v[48:51], v30 offset:21520
	ds_read_b128 v[52:55], v30 offset:37888
	ds_read_b128 v[56:59], v30 offset:37904
	ds_read_b128 v[60:63], v30 offset:5120
	ds_read_b128 v[64:67], v30 offset:5136
	ds_read_b32 v15, v31 offset:43520
	ds_read_b64 v[18:19], v32 offset:45216
	s_waitcnt lgkmcnt(10)
	v_pk_mul_f32 v[10:11], v[2:3], v[68:69]
	v_pk_fma_f32 v[10:11], v[4:5], v[70:71], v[10:11]
	v_pk_fma_f32 v[2:3], v[76:77], v[16:17], v[2:3] op_sel:[0,1,0]
	v_pk_fma_f32 v[10:11], v[6:7], v[72:73], v[10:11]
	v_pk_fma_f32 v[4:5], v[78:79], v[16:17], v[4:5] op_sel:[0,1,0]
	v_pk_fma_f32 v[10:11], v[8:9], v[74:75], v[10:11]
	v_pk_fma_f32 v[6:7], v[80:81], v[16:17], v[6:7] op_sel:[0,1,0]
	v_pk_fma_f32 v[10:11], v[16:17], v[20:21], v[10:11]
	v_pk_fma_f32 v[8:9], v[82:83], v[16:17], v[8:9] op_sel:[0,1,0]
	v_add_f32_e32 v10, v10, v11
	v_pk_fma_f32 v[2:3], v[84:85], v[16:17], v[2:3] op_sel_hi:[1,0,1]
	v_pk_fma_f32 v[4:5], v[86:87], v[16:17], v[4:5] op_sel_hi:[1,0,1]
	v_add_f32_dpp v10, v10, v10 quad_perm:[1,0,3,2] row_mask:0xf bank_mask:0xf
	v_pk_fma_f32 v[6:7], v[88:89], v[16:17], v[6:7] op_sel_hi:[1,0,1]
	v_pk_fma_f32 v[8:9], v[90:91], v[16:17], v[8:9] op_sel_hi:[1,0,1]
	v_add_f32_dpp v10, v10, v10 quad_perm:[2,3,0,1] row_mask:0xf bank_mask:0xf
	v_pk_mul_f32 v[12:13], v[2:3], v[134:135]
	v_pk_fma_f32 v[12:13], v[4:5], v[136:137], v[12:13]
	v_add_f32_dpp v14, v10, v10 row_half_mirror row_mask:0xf bank_mask:0xf
	v_pk_fma_f32 v[12:13], v[6:7], v[138:139], v[12:13]
	v_pk_fma_f32 v[12:13], v[8:9], v[140:141], v[12:13]
	v_add_f32_e32 v25, v12, v13
	ds_read_b128 v[68:71], v30 offset:29952
	ds_read_b128 v[72:75], v30 offset:29968
	ds_read_b128 v[76:79], v30 offset:21760
	ds_read_b128 v[80:83], v30 offset:21776
	ds_read_b128 v[84:87], v30 offset:38144
	ds_read_b128 v[88:91], v30 offset:38160
	ds_read_b128 v[134:137], v30 offset:5376
	ds_read_b128 v[138:141], v30 offset:5392
	ds_read_b32 v17, v31 offset:43648
	ds_read_b64 v[20:21], v32 offset:45224
	s_waitcnt lgkmcnt(10)
	v_pk_mul_f32 v[10:11], v[2:3], v[36:37]
	v_pk_fma_f32 v[10:11], v[4:5], v[38:39], v[10:11]
	v_cndmask_b32_e64 v26, v22, v23, s[6:7]
	v_cndmask_b32_e64 v27, v23, v22, s[6:7]
	v_pk_fma_f32 v[2:3], v[44:45], v[14:15], v[2:3] op_sel:[0,1,0]
	v_pk_fma_f32 v[10:11], v[6:7], v[40:41], v[10:11]
	v_cndmask_b32_e64 v29, v25, v24, s[6:7]
	v_cndmask_b32_e64 v28, v24, v25, s[6:7]
	v_pk_fma_f32 v[4:5], v[46:47], v[14:15], v[4:5] op_sel:[0,1,0]
	v_pk_fma_f32 v[10:11], v[8:9], v[42:43], v[10:11]
	v_add_f32_dpp v26, v27, v26 quad_perm:[1,0,3,2] row_mask:0xf bank_mask:0xf
	v_pk_fma_f32 v[6:7], v[48:49], v[14:15], v[6:7] op_sel:[0,1,0]
	v_add_f32_dpp v28, v29, v28 quad_perm:[1,0,3,2] row_mask:0xf bank_mask:0xf
	v_pk_fma_f32 v[10:11], v[14:15], v[18:19], v[10:11]
	v_pk_fma_f32 v[8:9], v[50:51], v[14:15], v[8:9] op_sel:[0,1,0]
	v_cndmask_b32_e64 v27, v26, v28, s[10:11]
	v_cndmask_b32_e64 v29, v28, v26, s[10:11]
	v_add_f32_e32 v10, v10, v11
	v_pk_fma_f32 v[2:3], v[52:53], v[14:15], v[2:3] op_sel_hi:[1,0,1]
	v_add_f32_dpp v27, v29, v27 quad_perm:[2,3,0,1] row_mask:0xf bank_mask:0xf
	v_pk_fma_f32 v[4:5], v[54:55], v[14:15], v[4:5] op_sel_hi:[1,0,1]
	v_add_f32_dpp v10, v10, v10 quad_perm:[1,0,3,2] row_mask:0xf bank_mask:0xf
	v_pk_fma_f32 v[6:7], v[56:57], v[14:15], v[6:7] op_sel_hi:[1,0,1]
	v_add_f32_dpp v27, v27, v27 row_shl:4 row_mask:0xf bank_mask:0xf
	v_pk_fma_f32 v[8:9], v[58:59], v[14:15], v[8:9] op_sel_hi:[1,0,1]
	v_add_f32_dpp v10, v10, v10 quad_perm:[2,3,0,1] row_mask:0xf bank_mask:0xf
	v_pk_mul_f32 v[12:13], v[2:3], v[60:61]
	v_pk_fma_f32 v[12:13], v[4:5], v[62:63], v[12:13]
	v_add_f32_dpp v16, v10, v10 row_half_mirror row_mask:0xf bank_mask:0xf
	ds_write_b32 v33, v27 offset:2048
	v_pk_fma_f32 v[12:13], v[6:7], v[64:65], v[12:13]
	v_pk_fma_f32 v[12:13], v[8:9], v[66:67], v[12:13]
	v_add_f32_e32 v22, v12, v13
	ds_read_b128 v[36:39], v30 offset:30208
	ds_read_b128 v[40:43], v30 offset:30224
	ds_read_b128 v[44:47], v30 offset:22016
	ds_read_b128 v[48:51], v30 offset:22032
	ds_read_b128 v[52:55], v30 offset:38400
	ds_read_b128 v[56:59], v30 offset:38416
	ds_read_b128 v[60:63], v30 offset:5632
	ds_read_b128 v[64:67], v30 offset:5648
	ds_read_b32 v15, v31 offset:43776
	ds_read_b64 v[18:19], v32 offset:45232
	s_waitcnt lgkmcnt(10)
	v_pk_mul_f32 v[10:11], v[2:3], v[68:69]
	v_pk_fma_f32 v[10:11], v[4:5], v[70:71], v[10:11]
	v_pk_fma_f32 v[2:3], v[76:77], v[16:17], v[2:3] op_sel:[0,1,0]
	v_pk_fma_f32 v[10:11], v[6:7], v[72:73], v[10:11]
	v_pk_fma_f32 v[4:5], v[78:79], v[16:17], v[4:5] op_sel:[0,1,0]
	v_pk_fma_f32 v[10:11], v[8:9], v[74:75], v[10:11]
	v_pk_fma_f32 v[6:7], v[80:81], v[16:17], v[6:7] op_sel:[0,1,0]
	v_pk_fma_f32 v[10:11], v[16:17], v[20:21], v[10:11]
	v_pk_fma_f32 v[8:9], v[82:83], v[16:17], v[8:9] op_sel:[0,1,0]
	v_add_f32_e32 v10, v10, v11
	v_pk_fma_f32 v[2:3], v[84:85], v[16:17], v[2:3] op_sel_hi:[1,0,1]
	v_pk_fma_f32 v[4:5], v[86:87], v[16:17], v[4:5] op_sel_hi:[1,0,1]
	v_add_f32_dpp v10, v10, v10 quad_perm:[1,0,3,2] row_mask:0xf bank_mask:0xf
	v_pk_fma_f32 v[6:7], v[88:89], v[16:17], v[6:7] op_sel_hi:[1,0,1]
	v_pk_fma_f32 v[8:9], v[90:91], v[16:17], v[8:9] op_sel_hi:[1,0,1]
	v_add_f32_dpp v10, v10, v10 quad_perm:[2,3,0,1] row_mask:0xf bank_mask:0xf
	v_pk_mul_f32 v[12:13], v[2:3], v[134:135]
	v_pk_fma_f32 v[12:13], v[4:5], v[136:137], v[12:13]
	v_add_f32_dpp v14, v10, v10 row_half_mirror row_mask:0xf bank_mask:0xf
	v_pk_fma_f32 v[12:13], v[6:7], v[138:139], v[12:13]
	v_pk_fma_f32 v[12:13], v[8:9], v[140:141], v[12:13]
	v_add_f32_e32 v23, v12, v13
	ds_read_b128 v[68:71], v30 offset:30464
	ds_read_b128 v[72:75], v30 offset:30480
	ds_read_b128 v[76:79], v30 offset:22272
	ds_read_b128 v[80:83], v30 offset:22288
	ds_read_b128 v[84:87], v30 offset:38656
	ds_read_b128 v[88:91], v30 offset:38672
	ds_read_b128 v[134:137], v30 offset:5888
	ds_read_b128 v[138:141], v30 offset:5904
	ds_read_b32 v17, v31 offset:43904
	ds_read_b64 v[20:21], v32 offset:45240
	s_waitcnt lgkmcnt(10)
	v_pk_mul_f32 v[10:11], v[2:3], v[36:37]
	v_pk_fma_f32 v[10:11], v[4:5], v[38:39], v[10:11]
	v_pk_fma_f32 v[2:3], v[44:45], v[14:15], v[2:3] op_sel:[0,1,0]
	v_pk_fma_f32 v[10:11], v[6:7], v[40:41], v[10:11]
	v_pk_fma_f32 v[4:5], v[46:47], v[14:15], v[4:5] op_sel:[0,1,0]
	v_pk_fma_f32 v[10:11], v[8:9], v[42:43], v[10:11]
	v_pk_fma_f32 v[6:7], v[48:49], v[14:15], v[6:7] op_sel:[0,1,0]
	v_pk_fma_f32 v[10:11], v[14:15], v[18:19], v[10:11]
	v_pk_fma_f32 v[8:9], v[50:51], v[14:15], v[8:9] op_sel:[0,1,0]
	v_add_f32_e32 v10, v10, v11
	v_pk_fma_f32 v[2:3], v[52:53], v[14:15], v[2:3] op_sel_hi:[1,0,1]
	v_pk_fma_f32 v[4:5], v[54:55], v[14:15], v[4:5] op_sel_hi:[1,0,1]
	v_add_f32_dpp v10, v10, v10 quad_perm:[1,0,3,2] row_mask:0xf bank_mask:0xf
	v_pk_fma_f32 v[6:7], v[56:57], v[14:15], v[6:7] op_sel_hi:[1,0,1]
	v_pk_fma_f32 v[8:9], v[58:59], v[14:15], v[8:9] op_sel_hi:[1,0,1]
	v_add_f32_dpp v10, v10, v10 quad_perm:[2,3,0,1] row_mask:0xf bank_mask:0xf
	v_pk_mul_f32 v[12:13], v[2:3], v[60:61]
	v_pk_fma_f32 v[12:13], v[4:5], v[62:63], v[12:13]
	v_add_f32_dpp v16, v10, v10 row_half_mirror row_mask:0xf bank_mask:0xf
	v_pk_fma_f32 v[12:13], v[6:7], v[64:65], v[12:13]
	v_pk_fma_f32 v[12:13], v[8:9], v[66:67], v[12:13]
	v_add_f32_e32 v24, v12, v13
	ds_read_b128 v[36:39], v30 offset:30720
	ds_read_b128 v[40:43], v30 offset:30736
	ds_read_b128 v[44:47], v30 offset:22528
	ds_read_b128 v[48:51], v30 offset:22544
	ds_read_b128 v[52:55], v30 offset:38912
	ds_read_b128 v[56:59], v30 offset:38928
	ds_read_b128 v[60:63], v30 offset:6144
	ds_read_b128 v[64:67], v30 offset:6160
	ds_read_b32 v15, v31 offset:44032
	ds_read_b64 v[18:19], v32 offset:45248
	s_waitcnt lgkmcnt(10)
	v_pk_mul_f32 v[10:11], v[2:3], v[68:69]
	v_pk_fma_f32 v[10:11], v[4:5], v[70:71], v[10:11]
	v_pk_fma_f32 v[2:3], v[76:77], v[16:17], v[2:3] op_sel:[0,1,0]
	v_pk_fma_f32 v[10:11], v[6:7], v[72:73], v[10:11]
	v_pk_fma_f32 v[4:5], v[78:79], v[16:17], v[4:5] op_sel:[0,1,0]
	v_pk_fma_f32 v[10:11], v[8:9], v[74:75], v[10:11]
	v_pk_fma_f32 v[6:7], v[80:81], v[16:17], v[6:7] op_sel:[0,1,0]
	v_pk_fma_f32 v[10:11], v[16:17], v[20:21], v[10:11]
	v_pk_fma_f32 v[8:9], v[82:83], v[16:17], v[8:9] op_sel:[0,1,0]
	v_add_f32_e32 v10, v10, v11
	v_pk_fma_f32 v[2:3], v[84:85], v[16:17], v[2:3] op_sel_hi:[1,0,1]
	v_pk_fma_f32 v[4:5], v[86:87], v[16:17], v[4:5] op_sel_hi:[1,0,1]
	v_add_f32_dpp v10, v10, v10 quad_perm:[1,0,3,2] row_mask:0xf bank_mask:0xf
	v_pk_fma_f32 v[6:7], v[88:89], v[16:17], v[6:7] op_sel_hi:[1,0,1]
	v_pk_fma_f32 v[8:9], v[90:91], v[16:17], v[8:9] op_sel_hi:[1,0,1]
	v_add_f32_dpp v10, v10, v10 quad_perm:[2,3,0,1] row_mask:0xf bank_mask:0xf
	v_pk_mul_f32 v[12:13], v[2:3], v[134:135]
	v_pk_fma_f32 v[12:13], v[4:5], v[136:137], v[12:13]
	v_add_f32_dpp v14, v10, v10 row_half_mirror row_mask:0xf bank_mask:0xf
	v_pk_fma_f32 v[12:13], v[6:7], v[138:139], v[12:13]
	v_pk_fma_f32 v[12:13], v[8:9], v[140:141], v[12:13]
	v_add_f32_e32 v25, v12, v13
	ds_read_b128 v[68:71], v30 offset:30976
	ds_read_b128 v[72:75], v30 offset:30992
	ds_read_b128 v[76:79], v30 offset:22784
	ds_read_b128 v[80:83], v30 offset:22800
	ds_read_b128 v[84:87], v30 offset:39168
	ds_read_b128 v[88:91], v30 offset:39184
	ds_read_b128 v[134:137], v30 offset:6400
	ds_read_b128 v[138:141], v30 offset:6416
	ds_read_b32 v17, v31 offset:44160
	ds_read_b64 v[20:21], v32 offset:45256
	s_waitcnt lgkmcnt(10)
	v_pk_mul_f32 v[10:11], v[2:3], v[36:37]
	v_pk_fma_f32 v[10:11], v[4:5], v[38:39], v[10:11]
	v_cndmask_b32_e64 v26, v22, v23, s[6:7]
	v_cndmask_b32_e64 v27, v23, v22, s[6:7]
	v_pk_fma_f32 v[2:3], v[44:45], v[14:15], v[2:3] op_sel:[0,1,0]
	v_pk_fma_f32 v[10:11], v[6:7], v[40:41], v[10:11]
	v_cndmask_b32_e64 v29, v25, v24, s[6:7]
	v_cndmask_b32_e64 v28, v24, v25, s[6:7]
	v_pk_fma_f32 v[4:5], v[46:47], v[14:15], v[4:5] op_sel:[0,1,0]
	v_pk_fma_f32 v[10:11], v[8:9], v[42:43], v[10:11]
	v_add_f32_dpp v26, v27, v26 quad_perm:[1,0,3,2] row_mask:0xf bank_mask:0xf
	v_pk_fma_f32 v[6:7], v[48:49], v[14:15], v[6:7] op_sel:[0,1,0]
	v_add_f32_dpp v28, v29, v28 quad_perm:[1,0,3,2] row_mask:0xf bank_mask:0xf
	v_pk_fma_f32 v[10:11], v[14:15], v[18:19], v[10:11]
	v_pk_fma_f32 v[8:9], v[50:51], v[14:15], v[8:9] op_sel:[0,1,0]
	v_cndmask_b32_e64 v27, v26, v28, s[10:11]
	v_cndmask_b32_e64 v29, v28, v26, s[10:11]
	v_add_f32_e32 v10, v10, v11
	v_pk_fma_f32 v[2:3], v[52:53], v[14:15], v[2:3] op_sel_hi:[1,0,1]
	v_add_f32_dpp v27, v29, v27 quad_perm:[2,3,0,1] row_mask:0xf bank_mask:0xf
	v_pk_fma_f32 v[4:5], v[54:55], v[14:15], v[4:5] op_sel_hi:[1,0,1]
	v_add_f32_dpp v10, v10, v10 quad_perm:[1,0,3,2] row_mask:0xf bank_mask:0xf
	v_pk_fma_f32 v[6:7], v[56:57], v[14:15], v[6:7] op_sel_hi:[1,0,1]
	v_add_f32_dpp v27, v27, v27 row_shl:4 row_mask:0xf bank_mask:0xf
	v_pk_fma_f32 v[8:9], v[58:59], v[14:15], v[8:9] op_sel_hi:[1,0,1]
	v_add_f32_dpp v10, v10, v10 quad_perm:[2,3,0,1] row_mask:0xf bank_mask:0xf
	v_pk_mul_f32 v[12:13], v[2:3], v[60:61]
	v_pk_fma_f32 v[12:13], v[4:5], v[62:63], v[12:13]
	v_add_f32_dpp v16, v10, v10 row_half_mirror row_mask:0xf bank_mask:0xf
	ds_write_b32 v33, v27 offset:2560
	v_pk_fma_f32 v[12:13], v[6:7], v[64:65], v[12:13]
	v_pk_fma_f32 v[12:13], v[8:9], v[66:67], v[12:13]
	v_add_f32_e32 v22, v12, v13
	ds_read_b128 v[36:39], v30 offset:31232
	ds_read_b128 v[40:43], v30 offset:31248
	ds_read_b128 v[44:47], v30 offset:23040
	ds_read_b128 v[48:51], v30 offset:23056
	ds_read_b128 v[52:55], v30 offset:39424
	ds_read_b128 v[56:59], v30 offset:39440
	ds_read_b128 v[60:63], v30 offset:6656
	ds_read_b128 v[64:67], v30 offset:6672
	ds_read_b32 v15, v31 offset:44288
	ds_read_b64 v[18:19], v32 offset:45264
	s_waitcnt lgkmcnt(10)
	v_pk_mul_f32 v[10:11], v[2:3], v[68:69]
	v_pk_fma_f32 v[10:11], v[4:5], v[70:71], v[10:11]
	v_pk_fma_f32 v[2:3], v[76:77], v[16:17], v[2:3] op_sel:[0,1,0]
	v_pk_fma_f32 v[10:11], v[6:7], v[72:73], v[10:11]
	v_pk_fma_f32 v[4:5], v[78:79], v[16:17], v[4:5] op_sel:[0,1,0]
	v_pk_fma_f32 v[10:11], v[8:9], v[74:75], v[10:11]
	v_pk_fma_f32 v[6:7], v[80:81], v[16:17], v[6:7] op_sel:[0,1,0]
	v_pk_fma_f32 v[10:11], v[16:17], v[20:21], v[10:11]
	v_pk_fma_f32 v[8:9], v[82:83], v[16:17], v[8:9] op_sel:[0,1,0]
	v_add_f32_e32 v10, v10, v11
	v_pk_fma_f32 v[2:3], v[84:85], v[16:17], v[2:3] op_sel_hi:[1,0,1]
	v_pk_fma_f32 v[4:5], v[86:87], v[16:17], v[4:5] op_sel_hi:[1,0,1]
	v_add_f32_dpp v10, v10, v10 quad_perm:[1,0,3,2] row_mask:0xf bank_mask:0xf
	v_pk_fma_f32 v[6:7], v[88:89], v[16:17], v[6:7] op_sel_hi:[1,0,1]
	v_pk_fma_f32 v[8:9], v[90:91], v[16:17], v[8:9] op_sel_hi:[1,0,1]
	v_add_f32_dpp v10, v10, v10 quad_perm:[2,3,0,1] row_mask:0xf bank_mask:0xf
	v_pk_mul_f32 v[12:13], v[2:3], v[134:135]
	v_pk_fma_f32 v[12:13], v[4:5], v[136:137], v[12:13]
	v_add_f32_dpp v14, v10, v10 row_half_mirror row_mask:0xf bank_mask:0xf
	v_pk_fma_f32 v[12:13], v[6:7], v[138:139], v[12:13]
	v_pk_fma_f32 v[12:13], v[8:9], v[140:141], v[12:13]
	v_add_f32_e32 v23, v12, v13
	ds_read_b128 v[68:71], v30 offset:31488
	ds_read_b128 v[72:75], v30 offset:31504
	ds_read_b128 v[76:79], v30 offset:23296
	ds_read_b128 v[80:83], v30 offset:23312
	ds_read_b128 v[84:87], v30 offset:39680
	ds_read_b128 v[88:91], v30 offset:39696
	ds_read_b128 v[134:137], v30 offset:6912
	ds_read_b128 v[138:141], v30 offset:6928
	ds_read_b32 v17, v31 offset:44416
	ds_read_b64 v[20:21], v32 offset:45272
	s_waitcnt lgkmcnt(10)
	v_pk_mul_f32 v[10:11], v[2:3], v[36:37]
	v_pk_fma_f32 v[10:11], v[4:5], v[38:39], v[10:11]
	v_pk_fma_f32 v[2:3], v[44:45], v[14:15], v[2:3] op_sel:[0,1,0]
	v_pk_fma_f32 v[10:11], v[6:7], v[40:41], v[10:11]
	v_pk_fma_f32 v[4:5], v[46:47], v[14:15], v[4:5] op_sel:[0,1,0]
	v_pk_fma_f32 v[10:11], v[8:9], v[42:43], v[10:11]
	v_pk_fma_f32 v[6:7], v[48:49], v[14:15], v[6:7] op_sel:[0,1,0]
	v_pk_fma_f32 v[10:11], v[14:15], v[18:19], v[10:11]
	v_pk_fma_f32 v[8:9], v[50:51], v[14:15], v[8:9] op_sel:[0,1,0]
	v_add_f32_e32 v10, v10, v11
	v_pk_fma_f32 v[2:3], v[52:53], v[14:15], v[2:3] op_sel_hi:[1,0,1]
	v_pk_fma_f32 v[4:5], v[54:55], v[14:15], v[4:5] op_sel_hi:[1,0,1]
	v_add_f32_dpp v10, v10, v10 quad_perm:[1,0,3,2] row_mask:0xf bank_mask:0xf
	v_pk_fma_f32 v[6:7], v[56:57], v[14:15], v[6:7] op_sel_hi:[1,0,1]
	v_pk_fma_f32 v[8:9], v[58:59], v[14:15], v[8:9] op_sel_hi:[1,0,1]
	v_add_f32_dpp v10, v10, v10 quad_perm:[2,3,0,1] row_mask:0xf bank_mask:0xf
	v_pk_mul_f32 v[12:13], v[2:3], v[60:61]
	v_pk_fma_f32 v[12:13], v[4:5], v[62:63], v[12:13]
	v_add_f32_dpp v16, v10, v10 row_half_mirror row_mask:0xf bank_mask:0xf
	v_pk_fma_f32 v[12:13], v[6:7], v[64:65], v[12:13]
	v_pk_fma_f32 v[12:13], v[8:9], v[66:67], v[12:13]
	v_add_f32_e32 v24, v12, v13
	ds_read_b128 v[36:39], v30 offset:31744
	ds_read_b128 v[40:43], v30 offset:31760
	ds_read_b128 v[44:47], v30 offset:23552
	ds_read_b128 v[48:51], v30 offset:23568
	ds_read_b128 v[52:55], v30 offset:39936
	ds_read_b128 v[56:59], v30 offset:39952
	ds_read_b128 v[60:63], v30 offset:7168
	ds_read_b128 v[64:67], v30 offset:7184
	ds_read_b32 v15, v31 offset:44544
	ds_read_b64 v[18:19], v32 offset:45280
	s_waitcnt lgkmcnt(10)
	v_pk_mul_f32 v[10:11], v[2:3], v[68:69]
	v_pk_fma_f32 v[10:11], v[4:5], v[70:71], v[10:11]
	v_pk_fma_f32 v[2:3], v[76:77], v[16:17], v[2:3] op_sel:[0,1,0]
	v_pk_fma_f32 v[10:11], v[6:7], v[72:73], v[10:11]
	v_pk_fma_f32 v[4:5], v[78:79], v[16:17], v[4:5] op_sel:[0,1,0]
	v_pk_fma_f32 v[10:11], v[8:9], v[74:75], v[10:11]
	v_pk_fma_f32 v[6:7], v[80:81], v[16:17], v[6:7] op_sel:[0,1,0]
	v_pk_fma_f32 v[10:11], v[16:17], v[20:21], v[10:11]
	v_pk_fma_f32 v[8:9], v[82:83], v[16:17], v[8:9] op_sel:[0,1,0]
	v_add_f32_e32 v10, v10, v11
	v_pk_fma_f32 v[2:3], v[84:85], v[16:17], v[2:3] op_sel_hi:[1,0,1]
	v_pk_fma_f32 v[4:5], v[86:87], v[16:17], v[4:5] op_sel_hi:[1,0,1]
	v_add_f32_dpp v10, v10, v10 quad_perm:[1,0,3,2] row_mask:0xf bank_mask:0xf
	v_pk_fma_f32 v[6:7], v[88:89], v[16:17], v[6:7] op_sel_hi:[1,0,1]
	v_pk_fma_f32 v[8:9], v[90:91], v[16:17], v[8:9] op_sel_hi:[1,0,1]
	v_add_f32_dpp v10, v10, v10 quad_perm:[2,3,0,1] row_mask:0xf bank_mask:0xf
	v_pk_mul_f32 v[12:13], v[2:3], v[134:135]
	v_pk_fma_f32 v[12:13], v[4:5], v[136:137], v[12:13]
	v_add_f32_dpp v14, v10, v10 row_half_mirror row_mask:0xf bank_mask:0xf
	v_pk_fma_f32 v[12:13], v[6:7], v[138:139], v[12:13]
	v_pk_fma_f32 v[12:13], v[8:9], v[140:141], v[12:13]
	v_add_f32_e32 v25, v12, v13
	ds_read_b128 v[68:71], v30 offset:32000
	ds_read_b128 v[72:75], v30 offset:32016
	ds_read_b128 v[76:79], v30 offset:23808
	ds_read_b128 v[80:83], v30 offset:23824
	ds_read_b128 v[84:87], v30 offset:40192
	ds_read_b128 v[88:91], v30 offset:40208
	ds_read_b128 v[134:137], v30 offset:7424
	ds_read_b128 v[138:141], v30 offset:7440
	ds_read_b32 v17, v31 offset:44672
	ds_read_b64 v[20:21], v32 offset:45288
	s_waitcnt lgkmcnt(10)
	v_pk_mul_f32 v[10:11], v[2:3], v[36:37]
	v_pk_fma_f32 v[10:11], v[4:5], v[38:39], v[10:11]
	v_cndmask_b32_e64 v26, v22, v23, s[6:7]
	v_cndmask_b32_e64 v27, v23, v22, s[6:7]
	v_pk_fma_f32 v[2:3], v[44:45], v[14:15], v[2:3] op_sel:[0,1,0]
	v_pk_fma_f32 v[10:11], v[6:7], v[40:41], v[10:11]
	v_cndmask_b32_e64 v29, v25, v24, s[6:7]
	v_cndmask_b32_e64 v28, v24, v25, s[6:7]
	v_pk_fma_f32 v[4:5], v[46:47], v[14:15], v[4:5] op_sel:[0,1,0]
	v_pk_fma_f32 v[10:11], v[8:9], v[42:43], v[10:11]
	v_add_f32_dpp v26, v27, v26 quad_perm:[1,0,3,2] row_mask:0xf bank_mask:0xf
	v_pk_fma_f32 v[6:7], v[48:49], v[14:15], v[6:7] op_sel:[0,1,0]
	v_add_f32_dpp v28, v29, v28 quad_perm:[1,0,3,2] row_mask:0xf bank_mask:0xf
	v_pk_fma_f32 v[10:11], v[14:15], v[18:19], v[10:11]
	v_pk_fma_f32 v[8:9], v[50:51], v[14:15], v[8:9] op_sel:[0,1,0]
	v_cndmask_b32_e64 v27, v26, v28, s[10:11]
	v_cndmask_b32_e64 v29, v28, v26, s[10:11]
	v_add_f32_e32 v10, v10, v11
	v_pk_fma_f32 v[2:3], v[52:53], v[14:15], v[2:3] op_sel_hi:[1,0,1]
	v_add_f32_dpp v27, v29, v27 quad_perm:[2,3,0,1] row_mask:0xf bank_mask:0xf
	v_pk_fma_f32 v[4:5], v[54:55], v[14:15], v[4:5] op_sel_hi:[1,0,1]
	v_add_f32_dpp v10, v10, v10 quad_perm:[1,0,3,2] row_mask:0xf bank_mask:0xf
	v_pk_fma_f32 v[6:7], v[56:57], v[14:15], v[6:7] op_sel_hi:[1,0,1]
	v_add_f32_dpp v27, v27, v27 row_shl:4 row_mask:0xf bank_mask:0xf
	v_pk_fma_f32 v[8:9], v[58:59], v[14:15], v[8:9] op_sel_hi:[1,0,1]
	v_add_f32_dpp v10, v10, v10 quad_perm:[2,3,0,1] row_mask:0xf bank_mask:0xf
	v_pk_mul_f32 v[12:13], v[2:3], v[60:61]
	v_pk_fma_f32 v[12:13], v[4:5], v[62:63], v[12:13]
	v_add_f32_dpp v16, v10, v10 row_half_mirror row_mask:0xf bank_mask:0xf
	ds_write_b32 v33, v27 offset:3072
	v_pk_fma_f32 v[12:13], v[6:7], v[64:65], v[12:13]
	v_pk_fma_f32 v[12:13], v[8:9], v[66:67], v[12:13]
	v_add_f32_e32 v22, v12, v13
	ds_read_b128 v[36:39], v30 offset:32256
	ds_read_b128 v[40:43], v30 offset:32272
	ds_read_b128 v[44:47], v30 offset:24064
	ds_read_b128 v[48:51], v30 offset:24080
	ds_read_b128 v[52:55], v30 offset:40448
	ds_read_b128 v[56:59], v30 offset:40464
	ds_read_b128 v[60:63], v30 offset:7680
	ds_read_b128 v[64:67], v30 offset:7696
	ds_read_b32 v15, v31 offset:44800
	ds_read_b64 v[18:19], v32 offset:45296
	s_waitcnt lgkmcnt(10)
	v_pk_mul_f32 v[10:11], v[2:3], v[68:69]
	v_pk_fma_f32 v[10:11], v[4:5], v[70:71], v[10:11]
	v_pk_fma_f32 v[2:3], v[76:77], v[16:17], v[2:3] op_sel:[0,1,0]
	v_pk_fma_f32 v[10:11], v[6:7], v[72:73], v[10:11]
	v_pk_fma_f32 v[4:5], v[78:79], v[16:17], v[4:5] op_sel:[0,1,0]
	v_pk_fma_f32 v[10:11], v[8:9], v[74:75], v[10:11]
	v_pk_fma_f32 v[6:7], v[80:81], v[16:17], v[6:7] op_sel:[0,1,0]
	v_pk_fma_f32 v[10:11], v[16:17], v[20:21], v[10:11]
	v_pk_fma_f32 v[8:9], v[82:83], v[16:17], v[8:9] op_sel:[0,1,0]
	v_add_f32_e32 v10, v10, v11
	v_pk_fma_f32 v[2:3], v[84:85], v[16:17], v[2:3] op_sel_hi:[1,0,1]
	v_pk_fma_f32 v[4:5], v[86:87], v[16:17], v[4:5] op_sel_hi:[1,0,1]
	v_add_f32_dpp v10, v10, v10 quad_perm:[1,0,3,2] row_mask:0xf bank_mask:0xf
	v_pk_fma_f32 v[6:7], v[88:89], v[16:17], v[6:7] op_sel_hi:[1,0,1]
	v_pk_fma_f32 v[8:9], v[90:91], v[16:17], v[8:9] op_sel_hi:[1,0,1]
	v_add_f32_dpp v10, v10, v10 quad_perm:[2,3,0,1] row_mask:0xf bank_mask:0xf
	v_pk_mul_f32 v[12:13], v[2:3], v[134:135]
	v_pk_fma_f32 v[12:13], v[4:5], v[136:137], v[12:13]
	v_add_f32_dpp v14, v10, v10 row_half_mirror row_mask:0xf bank_mask:0xf
	v_pk_fma_f32 v[12:13], v[6:7], v[138:139], v[12:13]
	v_pk_fma_f32 v[12:13], v[8:9], v[140:141], v[12:13]
	v_add_f32_e32 v23, v12, v13
	ds_read_b128 v[68:71], v30 offset:32512
	ds_read_b128 v[72:75], v30 offset:32528
	ds_read_b128 v[76:79], v30 offset:24320
	ds_read_b128 v[80:83], v30 offset:24336
	ds_read_b128 v[84:87], v30 offset:40704
	ds_read_b128 v[88:91], v30 offset:40720
	ds_read_b128 v[134:137], v30 offset:7936
	ds_read_b128 v[138:141], v30 offset:7952
	ds_read_b32 v17, v31 offset:44928
	ds_read_b64 v[20:21], v32 offset:45304
	s_waitcnt lgkmcnt(10)
	v_pk_mul_f32 v[10:11], v[2:3], v[36:37]
	v_pk_fma_f32 v[10:11], v[4:5], v[38:39], v[10:11]
	v_pk_fma_f32 v[2:3], v[44:45], v[14:15], v[2:3] op_sel:[0,1,0]
	v_pk_fma_f32 v[10:11], v[6:7], v[40:41], v[10:11]
	v_pk_fma_f32 v[4:5], v[46:47], v[14:15], v[4:5] op_sel:[0,1,0]
	v_pk_fma_f32 v[10:11], v[8:9], v[42:43], v[10:11]
	v_pk_fma_f32 v[6:7], v[48:49], v[14:15], v[6:7] op_sel:[0,1,0]
	v_pk_fma_f32 v[10:11], v[14:15], v[18:19], v[10:11]
	v_pk_fma_f32 v[8:9], v[50:51], v[14:15], v[8:9] op_sel:[0,1,0]
	v_add_f32_e32 v10, v10, v11
	v_pk_fma_f32 v[2:3], v[52:53], v[14:15], v[2:3] op_sel_hi:[1,0,1]
	v_pk_fma_f32 v[4:5], v[54:55], v[14:15], v[4:5] op_sel_hi:[1,0,1]
	v_add_f32_dpp v10, v10, v10 quad_perm:[1,0,3,2] row_mask:0xf bank_mask:0xf
	v_pk_fma_f32 v[6:7], v[56:57], v[14:15], v[6:7] op_sel_hi:[1,0,1]
	v_pk_fma_f32 v[8:9], v[58:59], v[14:15], v[8:9] op_sel_hi:[1,0,1]
	v_add_f32_dpp v10, v10, v10 quad_perm:[2,3,0,1] row_mask:0xf bank_mask:0xf
	v_pk_mul_f32 v[12:13], v[2:3], v[60:61]
	v_pk_fma_f32 v[12:13], v[4:5], v[62:63], v[12:13]
	v_add_f32_dpp v16, v10, v10 row_half_mirror row_mask:0xf bank_mask:0xf
	v_pk_fma_f32 v[12:13], v[6:7], v[64:65], v[12:13]
	v_pk_fma_f32 v[12:13], v[8:9], v[66:67], v[12:13]
	v_add_f32_e32 v24, v12, v13
	ds_read_b128 v[36:39], v30 offset:8192
	ds_read_b128 v[40:43], v30 offset:8208
	s_waitcnt lgkmcnt(2)
	v_pk_mul_f32 v[10:11], v[2:3], v[68:69]
	v_pk_fma_f32 v[10:11], v[4:5], v[70:71], v[10:11]
	v_pk_fma_f32 v[2:3], v[76:77], v[16:17], v[2:3] op_sel:[0,1,0]
	v_pk_fma_f32 v[10:11], v[6:7], v[72:73], v[10:11]
	v_pk_fma_f32 v[4:5], v[78:79], v[16:17], v[4:5] op_sel:[0,1,0]
	v_pk_fma_f32 v[10:11], v[8:9], v[74:75], v[10:11]
	v_pk_fma_f32 v[6:7], v[80:81], v[16:17], v[6:7] op_sel:[0,1,0]
	v_pk_fma_f32 v[10:11], v[16:17], v[20:21], v[10:11]
	v_pk_fma_f32 v[8:9], v[82:83], v[16:17], v[8:9] op_sel:[0,1,0]
	v_add_f32_e32 v10, v10, v11
	v_pk_fma_f32 v[2:3], v[84:85], v[16:17], v[2:3] op_sel_hi:[1,0,1]
	v_pk_fma_f32 v[4:5], v[86:87], v[16:17], v[4:5] op_sel_hi:[1,0,1]
	v_add_f32_dpp v10, v10, v10 quad_perm:[1,0,3,2] row_mask:0xf bank_mask:0xf
	v_pk_fma_f32 v[6:7], v[88:89], v[16:17], v[6:7] op_sel_hi:[1,0,1]
	v_pk_fma_f32 v[8:9], v[90:91], v[16:17], v[8:9] op_sel_hi:[1,0,1]
	v_add_f32_dpp v10, v10, v10 quad_perm:[2,3,0,1] row_mask:0xf bank_mask:0xf
	v_pk_mul_f32 v[12:13], v[2:3], v[134:135]
	v_pk_fma_f32 v[12:13], v[4:5], v[136:137], v[12:13]
	v_add_f32_dpp v14, v10, v10 row_half_mirror row_mask:0xf bank_mask:0xf
	v_pk_fma_f32 v[12:13], v[6:7], v[138:139], v[12:13]
	v_pk_fma_f32 v[12:13], v[8:9], v[140:141], v[12:13]
	v_add_f32_e32 v25, v12, v13
	v_cndmask_b32_e64 v26, v22, v23, s[6:7]
	v_cndmask_b32_e64 v27, v23, v22, s[6:7]
	v_cndmask_b32_e64 v29, v25, v24, s[6:7]
	v_cndmask_b32_e64 v28, v24, v25, s[6:7]
	v_add_f32_dpp v26, v27, v26 quad_perm:[1,0,3,2] row_mask:0xf bank_mask:0xf
	v_add_f32_dpp v28, v29, v28 quad_perm:[1,0,3,2] row_mask:0xf bank_mask:0xf
	v_cndmask_b32_e64 v27, v26, v28, s[10:11]
	v_cndmask_b32_e64 v29, v28, v26, s[10:11]
	s_waitcnt lgkmcnt(0)
	v_pk_mul_f32 v[2:3], v[2:3], v[36:37]
	v_pk_mul_f32 v[4:5], v[4:5], v[38:39]
	v_add_f32_dpp v27, v29, v27 quad_perm:[2,3,0,1] row_mask:0xf bank_mask:0xf
	v_pk_mul_f32 v[6:7], v[6:7], v[40:41]
	v_pk_mul_f32 v[8:9], v[8:9], v[42:43]
	v_add_f32_dpp v27, v27, v27 row_shl:4 row_mask:0xf bank_mask:0xf
	ds_write_b32 v33, v27 offset:3584
	s_add_i32 s0, s0, 1
	s_waitcnt lgkmcnt(0)
	s_barrier
	s_cmp_eq_u32 s0, 64
	s_cbranch_scc0 .Lscan_chunk
	s_branch .LBB0_496
